# mem-q to memory-attention hand-over: workgroup-local barrier with a single L1 invalidate before it (panel barrier skipped)
# baseline (speedup 1.0000x reference)
.LBB0_1131:
	v_readlane_b32 s0, v253, 27
	v_readlane_b32 s1, v253, 28
	s_and_b64 vcc, exec, s[0:1]
	s_cbranch_vccz .LBB0_1137
	s_xor_b64 s[2:3], s[84:85], -1
	s_mov_b64 s[0:1], -1
	s_and_b64 vcc, exec, s[2:3]
	s_cbranch_vccz .LBB0_1161
	s_waitcnt vmcnt(0)
	v_readlane_b32 s0, v252, 36
	s_add_i32 s26, s0, 1
	s_waitcnt vmcnt(0) lgkmcnt(0)
	s_add_i32 s2, s18, -1
	s_mul_hi_i32 s3, s2, 0x38e38e39
	s_lshr_b32 s4, s3, 31
	s_ashr_i32 s3, s3, 1
	s_add_i32 s3, s3, s4
	s_mul_i32 s3, s3, 9
	s_sub_i32 s2, s2, s3
	s_cmp_lg_u32 s2, 4
	s_cbranch_scc1 .Lpb_full
	s_mov_b32 s26, s0
	s_mov_b64 s[0:1], exec
	v_readlane_b32 s2, v251, 5
	v_readlane_b32 s3, v251, 6
	s_and_b64 s[2:3], s[0:1], s[2:3]
	s_mov_b64 exec, s[2:3]
	s_cbranch_execz .Lpb4_noinv
	buffer_inv sc1
	s_waitcnt vmcnt(0)
.Lpb4_noinv:
	s_mov_b64 exec, s[0:1]
	s_barrier
	s_mov_b64 s[0:1], 0
	s_branch .LBB0_1161
